# work-balance bracket: C2 contiguous ranges 7 rows per wave on the fifth-tile workgroups, 9 on the next 768 waves, 8 on the last 1024
# speedup vs baseline: 1.0006x; 1.0006x over previous
; __global__ void __launch_bounds__(NWAVES * 64, 2) mk_fwd(Args args) {
;     ...
;                 for (int m = gw; m < M; m += ngw) {
;                     const bool smp = m >= MP;
;                     const int b = smp ? ((m - MP) >> 5) : (m >> 12), t = smp ? ((m - MP) & 31) : (m & 4095);
;                     const int pos = smp ? PAST + t : t;
;                     const int T = smp ? DS : SEQ;
;                     const size_t lrow = smp ? (size_t)MP + (size_t)b * SKEYS + PAST + t : (size_t)m;
;                     float* lat_out = smp ? out + O_LATS + ((size_t)(l * DB + b) * DS + t) * KVL : out + O_LATP + ((size_t)(l * NB + b) * SEQ + t) * KVL;
;                     float* kr_out = smp ? out + O_KRS + ((size_t)(l * DB + b) * DS + t) * ROPE : out + O_KRP + ((size_t)(l * NB + b) * SEQ + t) * ROPE;
;                     const bf16_t* prow = proj + (size_t)m * NPAD;
.LBB0_498:
	v_readlane_b32 s36, v252, 4
	s_lshl_b64 s[2:3], s[48:49], 2
	v_readlane_b32 s42, v252, 10
	v_readlane_b32 s37, v252, 5
	v_readlane_b32 s43, v252, 11
	s_add_u32 s36, s42, s2
	v_readlane_b32 s38, v252, 6
	s_addc_u32 s37, s43, s3
	s_ashr_i32 s2, s10, 6
	s_lshl_b32 s3, s1, 3
	s_add_i32 s38, s3, s2
	s_cmp_lt_u32 s38, 0x100
	s_cbranch_scc0 .Lc2r_b
	s_mul_i32 s98, s38, 7
	s_add_i32 s99, s98, 6
	s_branch .Lc2r_done
.Lc2r_b:
	s_sub_i32 s99, s38, 0x100
	s_cmp_lt_u32 s99, 0x300
	s_cbranch_scc0 .Lc2r_c
	s_mul_i32 s98, s99, 9
	s_add_i32 s98, s98, 0x700
	s_add_i32 s99, s98, 8
	s_branch .Lc2r_done
.Lc2r_c:
	s_sub_i32 s99, s99, 0x300
	s_lshl_b32 s98, s99, 3
	s_add_i32 s98, s98, 0x2200
	s_add_i32 s99, s98, 7
